# bundle8 + P2/P11 process M-tiles in reverse order (pm xor 127) so the most recently written h tiles are read first (MALL hits)
# speedup vs baseline: 1.0074x; 1.0074x over previous
.LBB0_362:
	s_add_i32 s2, s6, s2
	s_lshr_b32 s5, s2, 5
	s_and_b32 s2, s2, 31
	s_lshl_b32 s5, s5, 2
	s_and_b32 s3, s2, 3
	s_add_i32 s79, s5, s3
	s_xor_b32 s79, s79, 127
	s_lshr_b32 s80, s2, 2
	s_andn2_b64 vcc, exec, s[0:1]
	s_cbranch_vccnz .LBB0_357

.LBB0_373:
	s_ashr_i32 s10, s42, 3
	s_add_i32 s10, s54, s10
	s_lshr_b32 s42, s10, 5
	s_lshl_b32 s42, s42, 2
	s_and_b32 s10, s10, 31
	s_lshr_b32 s77, s10, 2
	s_and_b32 s10, s10, 3
	s_add_i32 s78, s42, s10
	s_xor_b32 s78, s78, 127

.LBB0_1550:
	v_lshrrev_b32_e32 v4, 1, v0
	v_lshrrev_b32_e32 v5, 5, v0
	v_lshlrev_b32_e32 v1, 4, v0
	v_and_b32_e32 v2, 32, v0
	v_and_b32_e32 v4, 24, v4
	v_and_b32_e32 v5, 4, v5
	v_bfe_u32 v6, v0, 2, 2
	v_bfe_u32 v3, v0, 2, 4
	v_bitop3_b32 v1, v1, v2, 48 bitop3:0x6c
	v_and_b32_e32 v10, 64, v0
	v_or3_b32 v4, v5, v6, v4
	v_lshrrev_b32_e32 v5, 3, v0
	v_or_b32_e32 v2, v1, v10
	v_and_or_b32 v6, v5, 48, v3
	v_and_or_b32 v5, v5, 32, v4
	v_lshrrev_b32_e32 v2, 1, v2
	v_mul_u32_u24_e32 v5, 0x1600, v5
	s_add_u32 s22, s26, 0x11c00000
	v_or_b32_e32 v5, v5, v2
	s_addc_u32 s23, s27, 0
	v_lshlrev_b32_e32 v130, 1, v5
	v_bfe_u32 v5, v0, 3, 25
	s_add_u32 s24, s26, 0x2d00000
	v_or_b32_e32 v5, 64, v5
	s_movk_i32 s1, 0x70
	s_addc_u32 s28, s27, 0
	v_and_or_b32 v3, v5, s1, v3
	s_movk_i32 s1, 0x60
	s_add_i32 s0, s4, s0
	v_and_or_b32 v4, v5, s1, v4
	s_lshr_b32 s6, s0, 5
	s_lshl_b32 s6, s6, 2
	s_and_b32 s7, s0, 28
	s_lshl_b32 s7, s7, 1
	s_and_b32 s0, s0, 3
	s_lshr_b32 s5, s2, 6
	s_add_i32 s44, s6, s0
	s_xor_b32 s44, s44, 127
	s_ashr_i32 s0, s7, 3
	s_lshr_b32 s3, s2, 8
	s_lshl_b32 s29, s5, 10
	s_lshr_b32 s4, s7, 3
	s_mul_hi_i32 s1, s0, 0x2c0000
	s_mul_i32 s0, s0, 0x2c0000
	v_mul_u32_u24_e32 v12, 0x1600, v3
	s_add_u32 s20, s24, s0
	v_or_b32_e32 v3, v12, v2
	s_addc_u32 s21, s28, s1
	s_add_i32 s30, s29, 0
	v_mul_u32_u24_e32 v11, 0x1600, v6
	v_lshlrev_b32_e32 v132, 1, v3
	v_mul_u32_u24_e32 v3, 0x1600, v4
	s_add_i32 m0, s30, 0x10000
	v_or_b32_e32 v6, v2, v11
	v_or_b32_e32 v2, v3, v2
	global_load_lds_dwordx4 v130, s[20:21]
	s_add_i32 m0, s30, 0x12000
	v_lshlrev_b32_e32 v134, 1, v2
	s_add_u32 s0, s20, 0x160000
	global_load_lds_dwordx4 v134, s[20:21]
	s_addc_u32 s1, s21, 0
	s_add_i32 m0, s30, 0x14000
	s_mul_i32 s8, s44, 0x2c0000
	global_load_lds_dwordx4 v130, s[0:1]
	s_add_i32 m0, s30, 0x16000
	s_mul_hi_i32 s6, s44, 0x2c0000
	s_add_u32 s16, s22, s8
	s_addc_u32 s17, s23, s6
	s_add_i32 s31, s30, 0x2000
	v_lshlrev_b32_e32 v128, 1, v6
	global_load_lds_dwordx4 v134, s[0:1]
	s_mov_b32 m0, s30
	s_add_u32 s0, s16, 0x160000
	global_load_lds_dwordx4 v128, s[16:17]
	s_mov_b32 m0, s31
	s_addc_u32 s1, s17, 0
	s_add_i32 s34, s30, 0x4000
	global_load_lds_dwordx4 v132, s[16:17]
	s_mov_b32 m0, s34
	s_add_i32 s35, s30, 0x6000
	global_load_lds_dwordx4 v128, s[0:1]
	s_mov_b32 m0, s35
	v_mov_b32_e32 v131, 0
	global_load_lds_dwordx4 v132, s[0:1]
	v_mov_b32_e32 v135, v131
	v_mov_b32_e32 v129, v131
	v_mov_b32_e32 v133, v131
	s_cmp_eq_u32 s3, 1
	s_mov_b32 s36, 0
	v_lshl_add_u64 v[8:9], s[20:21], 0, v[130:131]
	v_lshl_add_u64 v[6:7], s[20:21], 0, v[134:135]
	v_lshl_add_u64 v[2:3], s[16:17], 0, v[128:129]
	s_cselect_b64 s[0:1], -1, 0
	s_cmp_lg_u32 s3, 1
	v_lshl_add_u64 v[4:5], s[16:17], 0, v[132:133]
	s_cbranch_scc1 .LBB0_1552
	s_barrier

.LBB0_1560:
	s_ashr_i32 s2, s14, 3
	s_add_i32 s2, s26, s2
	s_lshr_b32 s14, s2, 5
	s_lshl_b32 s14, s14, 2
	s_and_b32 s2, s2, 31
	s_lshr_b32 s42, s2, 2
	s_and_b32 s2, s2, 3
	s_add_i32 s43, s14, s2
	s_xor_b32 s43, s43, 127
